# hg_out: removed four stale vmcnt(0) drains in the unit epilogue (gains are hoisted) and replaced output-stage per-fragment vmcnt waits by one vmcnt(34)/vmcnt(0) at stage head
# speedup vs baseline: 1.0048x; 1.0010x over previous
; DI unsigned pk2(float lo, float hi) { f32x2_t v = {lo, hi}; bf16x2_t b = __builtin_convertvector(v, bf16x2_t); return __builtin_bit_cast(unsigned, b); }
; DI float fexp(float x) { return __builtin_amdgcn_exp2f(x * LOG2E); }
; DI void hg_out_units(LAS unsigned char* L, int u0, int G, const float* LOGF, const bf16* QHG, const bf16* IHG, const bf16* GHG, const bf16* ST, const float* og, bf16* MIX, int tid, int wave, int lane) {
;     ...
;     __syncthreads();
;     const float r = rsqrtf((ssq[(16 * tt + lr) * 2] + ssq[(16 * tt + lr) * 2 + 1]) * (1.f / 128.f) + EPS);
;     const size_t tok = tok0 + 16 * tt + lr;
; #pragma unroll
;     for (int d = 0; d < 4; ++d) { const int dv0 = 16 * (4 * dh + d) + quad * 4;
;         const u32x2 gt = gtv[d]; const f32x4 gn = *(const f32x4*)(og + dv0);
;         float gv[4] = {__uint_as_float(gt.x << 16), __uint_as_float(gt.x & 0xffff0000u), __uint_as_float(gt.y << 16), __uint_as_float(gt.y & 0xffff0000u)};
;         float o[4];
; #pragma unroll
;         for (int j = 0; j < 4; ++j) o[j] = acc[d][j] * r * gn[j] * gv[j] * __builtin_amdgcn_rcpf(1.f + fexp(-gv[j]));
;         u32x2 w; w.x = pk2(o[0], o[1]); w.y = pk2(o[2], o[3]); *(u32x2*)(MIX + tok * DM + 1024 + h * 128 + dv0) = w; }
.LBB0_334:
	s_or_b64 exec, exec, vcc
	v_lshlrev_b64 v[14:15], 12, v[126:127]
	v_lshl_add_u64 v[14:15], v[84:85], 0, v[14:15]
	s_waitcnt lgkmcnt(0)
	s_barrier
	v_lshl_add_u64 v[18:19], v[14:15], 0, s[36:37]
	ds_read_b64 v[12:13], v172
	v_lshlrev_b32_e32 v20, 16, v124
	v_and_b32_e32 v21, 0xffff0000, v124
	v_mov_b32_e32 v117, v161
	s_mov_b64 s[84:85], 0xb000800
	s_waitcnt lgkmcnt(0)
	v_add_f32_e32 v12, v12, v13
	v_fmamk_f32 v12, v12, 0x3c000000, v203
	v_cmp_gt_f32_e32 vcc, s2, v12
	v_mul_f32_e32 v13, 0x4b800000, v12
	s_mov_b32 s25, 0xb000000
	v_cndmask_b32_e32 v12, v12, v13, vcc
	v_rsq_f32_e32 v12, v12
	s_add_i32 s95, s95, s40
	v_readlane_b32 s40, v254, 40
	v_readlane_b32 s41, v254, 41
	v_mul_f32_e32 v13, 0x45800000, v12
	v_cndmask_b32_e32 v12, v12, v13, vcc
	v_mul_f32_e32 v13, 0xbfb8aa3b, v20
	v_exp_f32_e32 v13, v13
	v_lshl_add_u64 v[108:109], v[108:109], 0, s[40:41]
	v_add_f32_e32 v13, 1.0, v13
	v_rcp_f32_e32 v22, v13
	v_pk_mul_f32 v[28:29], v[44:45], v[12:13] op_sel_hi:[1,0]
	v_mul_f32_e32 v13, 0xbfb8aa3b, v21
	v_exp_f32_e32 v13, v13
	v_pk_mul_f32 v[14:15], v[208:209], v[28:29]
	s_nop 0
	v_pk_mul_f32 v[14:15], v[14:15], v[20:21]
	v_add_f32_e32 v13, 1.0, v13
	v_lshlrev_b32_e32 v20, 16, v125
	v_rcp_f32_e32 v23, v13
	v_mul_f32_e32 v13, 0xbfb8aa3b, v20
	v_exp_f32_e32 v13, v13
	v_and_b32_e32 v21, 0xffff0000, v125
	v_pk_mul_f32 v[14:15], v[22:23], v[14:15]
	v_add_f32_e32 v13, 1.0, v13
	v_rcp_f32_e32 v22, v13
	v_pk_mul_f32 v[28:29], v[46:47], v[12:13] op_sel_hi:[1,0]
	v_mul_f32_e32 v13, 0xbfb8aa3b, v21
	v_exp_f32_e32 v13, v13
	v_pk_mul_f32 v[16:17], v[210:211], v[28:29]
	v_add_f32_e32 v13, 1.0, v13
	v_rcp_f32_e32 v23, v13
	v_pk_mul_f32 v[16:17], v[16:17], v[20:21]
	v_cvt_pk_bf16_f32 v20, v14, v15
	v_pk_mul_f32 v[16:17], v[22:23], v[16:17]
	s_nop 0
	v_cvt_pk_bf16_f32 v21, v16, v17
	v_lshl_add_u64 v[16:17], v[18:19], 0, v[116:117]
	v_lshl_add_u64 v[14:15], v[16:17], 0, s[84:85]
	v_add_co_u32_e32 v16, vcc, s25, v16
	v_readlane_b32 s25, v254, 24
	s_nop 0
	v_addc_co_u32_e32 v17, vcc, 0, v17, vcc
	global_store_dwordx2 v[16:17], v[20:21], off offset:2048
	v_lshlrev_b32_e32 v20, 16, v122
	v_mul_f32_e32 v13, 0xbfb8aa3b, v20
	v_exp_f32_e32 v13, v13
	v_and_b32_e32 v21, 0xffff0000, v122
	s_add_i32 s96, s96, s25
	s_andn2_b64 vcc, exec, s[86:87]
	v_add_f32_e32 v13, 1.0, v13
	v_rcp_f32_e32 v22, v13
	v_pk_mul_f32 v[28:29], v[32:33], v[12:13] op_sel_hi:[1,0]
	v_mul_f32_e32 v13, 0xbfb8aa3b, v21
	v_exp_f32_e32 v13, v13
	v_pk_mul_f32 v[16:17], v[212:213], v[28:29]
	s_nop 0
	v_pk_mul_f32 v[16:17], v[16:17], v[20:21]
	v_add_f32_e32 v13, 1.0, v13
	v_lshlrev_b32_e32 v20, 16, v123
	v_rcp_f32_e32 v23, v13
	v_mul_f32_e32 v13, 0xbfb8aa3b, v20
	v_exp_f32_e32 v13, v13
	v_and_b32_e32 v21, 0xffff0000, v123
	v_pk_mul_f32 v[16:17], v[22:23], v[16:17]
	v_add_f32_e32 v13, 1.0, v13
	v_rcp_f32_e32 v22, v13
	v_pk_mul_f32 v[28:29], v[34:35], v[12:13] op_sel_hi:[1,0]
	v_mul_f32_e32 v13, 0xbfb8aa3b, v21
	v_exp_f32_e32 v13, v13
	v_pk_mul_f32 v[18:19], v[214:215], v[28:29]
	v_cvt_pk_bf16_f32 v16, v16, v17
	v_pk_mul_f32 v[18:19], v[18:19], v[20:21]
	v_add_f32_e32 v13, 1.0, v13
	v_rcp_f32_e32 v23, v13
	v_lshlrev_b32_e32 v20, 16, v120
	v_mul_f32_e32 v13, 0xbfb8aa3b, v20
	v_exp_f32_e32 v13, v13
	v_pk_mul_f32 v[18:19], v[22:23], v[18:19]
	v_and_b32_e32 v21, 0xffff0000, v120
	v_cvt_pk_bf16_f32 v17, v18, v19
	global_store_dwordx2 v[14:15], v[16:17], off offset:32
	v_add_f32_e32 v13, 1.0, v13
	v_rcp_f32_e32 v22, v13
	v_pk_mul_f32 v[24:25], v[24:25], v[12:13] op_sel_hi:[1,0]
	v_mul_f32_e32 v13, 0xbfb8aa3b, v21
	v_exp_f32_e32 v13, v13
	v_pk_mul_f32 v[16:17], v[216:217], v[24:25]
	s_nop 0
	v_pk_mul_f32 v[16:17], v[16:17], v[20:21]
	v_add_f32_e32 v13, 1.0, v13
	v_lshlrev_b32_e32 v20, 16, v121
	v_rcp_f32_e32 v23, v13
	v_mul_f32_e32 v13, 0xbfb8aa3b, v20
	v_exp_f32_e32 v13, v13
	v_and_b32_e32 v21, 0xffff0000, v121
	v_pk_mul_f32 v[16:17], v[22:23], v[16:17]
	v_add_f32_e32 v13, 1.0, v13
	v_rcp_f32_e32 v22, v13
	v_pk_mul_f32 v[24:25], v[26:27], v[12:13] op_sel_hi:[1,0]
	v_mul_f32_e32 v13, 0xbfb8aa3b, v21
	v_exp_f32_e32 v13, v13
	v_pk_mul_f32 v[18:19], v[218:219], v[24:25]
	v_cvt_pk_bf16_f32 v16, v16, v17
	v_pk_mul_f32 v[18:19], v[18:19], v[20:21]
	v_add_f32_e32 v13, 1.0, v13
	v_rcp_f32_e32 v23, v13
	v_lshlrev_b32_e32 v20, 16, v118
	v_mul_f32_e32 v13, 0xbfb8aa3b, v20
	v_exp_f32_e32 v13, v13
	v_pk_mul_f32 v[18:19], v[22:23], v[18:19]
	v_and_b32_e32 v21, 0xffff0000, v118
	v_cvt_pk_bf16_f32 v17, v18, v19
	global_store_dwordx2 v[14:15], v[16:17], off offset:64
	v_add_f32_e32 v13, 1.0, v13
	v_rcp_f32_e32 v22, v13
	v_pk_mul_f32 v[8:9], v[8:9], v[12:13] op_sel_hi:[1,0]
	v_mul_f32_e32 v13, 0xbfb8aa3b, v21
	v_exp_f32_e32 v13, v13
	v_pk_mul_f32 v[8:9], v[220:221], v[8:9]
	v_add_f32_e32 v13, 1.0, v13
	v_lshlrev_b32_e32 v16, 16, v119
	v_rcp_f32_e32 v23, v13
	v_mul_f32_e32 v13, 0xbfb8aa3b, v16
	v_exp_f32_e32 v13, v13
	v_and_b32_e32 v17, 0xffff0000, v119
	v_pk_mul_f32 v[8:9], v[8:9], v[20:21]
	v_add_f32_e32 v13, 1.0, v13
	v_pk_mul_f32 v[10:11], v[10:11], v[12:13] op_sel_hi:[1,0]
	v_mul_f32_e32 v12, 0xbfb8aa3b, v17
	v_exp_f32_e32 v12, v12
	v_rcp_f32_e32 v20, v13
	v_pk_mul_f32 v[10:11], v[222:223], v[10:11]
	v_pk_mul_f32 v[8:9], v[22:23], v[8:9]
	v_add_f32_e32 v12, 1.0, v12
	v_rcp_f32_e32 v21, v12
	v_pk_mul_f32 v[10:11], v[10:11], v[16:17]
	v_cvt_pk_bf16_f32 v8, v8, v9
	v_pk_mul_f32 v[10:11], v[20:21], v[10:11]
	s_nop 0
	v_cvt_pk_bf16_f32 v9, v10, v11
	global_store_dwordx2 v[14:15], v[8:9], off offset:96
	s_barrier
	s_cbranch_vccz .LBB0_351

; #define LAS __attribute__((address_space(3)))
; DI unsigned pk2(float lo, float hi) { f32x2_t v = {lo, hi}; bf16x2_t b = __builtin_convertvector(v, bf16x2_t); return __builtin_bit_cast(unsigned, b); }
; DI void hg_out_units(LAS unsigned char* L, int u0, int G, const float* LOGF, const bf16* QHG, const bf16* IHG, const bf16* GHG, const bf16* ST, const float* og, bf16* MIX, int tid, int wave, int lane) {
;     ...
;         u32x2 w; w.x = pk2(acc[0], acc[1]); w.y = pk2(acc[2], acc[3]); *(LAS u32x2*)(At + (16 * tt + lr) * 72 + 16 * st + quad * 4) = w; }
;     __syncthreads();
.LBB0_349:
	v_cvt_pk_bf16_f32 v72, v72, v73
	v_cvt_pk_bf16_f32 v73, v74, v75
	v_add_u32_e32 v74, s94, v146
	ds_write_b64 v74, v[72:73]
	s_waitcnt lgkmcnt(0)
	s_barrier
	s_and_b64 vcc, exec, s[86:87]
	s_cbranch_vccnz .Lhgo_last
	s_waitcnt vmcnt(34)
	s_branch .Lhgo_go

; #define LAS __attribute__((address_space(3)))
; DI float shflx(float v, int mask) { return __uint_as_float((unsigned)__builtin_amdgcn_ds_bpermute((lane_id_opaque() ^ mask) << 2, (int)__float_as_uint(v))); }
; DI void hg_out_units(LAS unsigned char* L, int u0, int G, const float* LOGF, const bf16* QHG, const bf16* IHG, const bf16* GHG, const bf16* ST, const float* og, bf16* MIX, int tid, int wave, int lane) {
;     ...
;     pg8::f32x4 acc[4];
;     bf16x8 bA[2], bQ[4];
; #pragma unroll
;     for (int ks = 0; ks < 2; ++ks) bA[ks] = *(const LAS bf16x8*)(At + (16 * tt + lr) * 72 + 32 * ks + quad * 8);
; #pragma unroll
;     for (int ks = 0; ks < 4; ++ks) bQ[ks] = *(const LAS bf16x8*)(Qh + (16 * tt + lr) * 136 + 32 * ks + quad * 8);
;     float ss = 0.f;
; #pragma unroll
;     for (int d = 0; d < 4; ++d) { const int dt = 4 * dh + d; acc[d] = (pg8::f32x4){0.f, 0.f, 0.f, 0.f};
; #pragma unroll
;         for (int ks = 0; ks < 2; ++ks) { const LAS bf16* vp = Vs + (32 * ks + quad * 8 + (lr >> 2)) * 160 + 16 * dt + 4 * (lr & 3);
;             const s16x4 lo = __builtin_bit_cast(s16x4, __builtin_amdgcn_ds_read_tr16_b64_v4i16((LAS v4i16_t*)vp)), hi = __builtin_bit_cast(s16x4, __builtin_amdgcn_ds_read_tr16_b64_v4i16((LAS v4i16_t*)(vp + 4 * 160)));
;             const bf16x8 a = __builtin_shufflevector(lo, hi, 0, 1, 2, 3, 4, 5, 6, 7); acc[d] = __builtin_amdgcn_mfma_f32_16x16x32_bf16(a, bA[ks], acc[d], 0, 0, 0); }
; #pragma unroll
;         for (int ks = 0; ks < 4; ++ks) acc[d] = __builtin_amdgcn_mfma_f32_16x16x32_bf16(stf[d][ks], bQ[ks], acc[d], 0, 0, 0);
;         ss += (acc[d][0] * acc[d][0] + acc[d][1] * acc[d][1]) + (acc[d][2] * acc[d][2] + acc[d][3] * acc[d][3]); }
;     ss += shflx(ss, 16); ss += shflx(ss, 32);
;     if (quad == 0) ssq[(16 * tt + lr) * 2 + dh] = ss;
.Lhgo_go:
	ds_read_b64_tr_b16 v[74:75], v171 offset:53504
	ds_read_b64_tr_b16 v[72:73], v171 offset:52224
	v_add_u32_e32 v76, v145, v100
	ds_read_b128 v[80:83], v76
	ds_read_b64_tr_b16 v[184:185], v171 offset:62464
	ds_read_b64_tr_b16 v[186:187], v171 offset:63744
	ds_read_b128 v[76:79], v76 offset:64
	s_waitcnt lgkmcnt(3)
	v_mfma_f32_16x16x32_bf16 v[72:75], v[72:75], v[80:83], 0
	s_mov_b32 s25, -1
	s_waitcnt lgkmcnt(0)
	v_mfma_f32_16x16x32_bf16 v[184:187], v[184:187], v[76:79], v[72:75]
	s_nop 4
	ds_read_b128 v[72:75], v147 offset:34816
	ds_read_b64_tr_b16 v[188:189], v171 offset:52256
	ds_read_b64_tr_b16 v[190:191], v171 offset:53536
	s_waitcnt lgkmcnt(2)
	v_mfma_f32_16x16x32_bf16 v[184:187], v[68:71], v[72:75], v[184:187]
	ds_read_b128 v[68:71], v147 offset:34880
	s_waitcnt lgkmcnt(0)
	v_mfma_f32_16x16x32_bf16 v[184:187], v[52:55], v[68:71], v[184:187]
	ds_read_b128 v[52:55], v147 offset:34944
	s_waitcnt lgkmcnt(0)
	v_mfma_f32_16x16x32_bf16 v[184:187], v[48:51], v[52:55], v[184:187]
	ds_read_b128 v[48:51], v147 offset:35008
	ds_read_b64_tr_b16 v[192:193], v171 offset:62496
	ds_read_b64_tr_b16 v[194:195], v171 offset:63776
	v_mfma_f32_16x16x32_bf16 v[188:191], v[188:191], v[80:83], 0
	s_waitcnt lgkmcnt(2)
	v_mfma_f32_16x16x32_bf16 v[44:47], v[44:47], v[48:51], v[184:187]
	s_waitcnt lgkmcnt(0)
	v_mfma_f32_16x16x32_bf16 v[184:187], v[192:195], v[76:79], v[188:191]
	v_mfma_f32_16x16x32_bf16 v[56:59], v[56:59], v[72:75], v[184:187]
	v_mfma_f32_16x16x32_bf16 v[56:59], v[60:63], v[68:71], v[56:59]
	ds_read_b64_tr_b16 v[60:61], v171 offset:52288
	v_mfma_f32_16x16x32_bf16 v[56:59], v[64:67], v[52:55], v[56:59]
	v_mfma_f32_16x16x32_bf16 v[32:35], v[32:35], v[48:51], v[56:59]
	ds_read_b64_tr_b16 v[62:63], v171 offset:53568
	s_nop 4
	ds_read_b64_tr_b16 v[56:57], v171 offset:62528
	ds_read_b64_tr_b16 v[58:59], v171 offset:63808
	s_waitcnt lgkmcnt(2)
	v_mfma_f32_16x16x32_bf16 v[60:63], v[60:63], v[80:83], 0
	s_waitcnt lgkmcnt(0)
	v_mfma_f32_16x16x32_bf16 v[56:59], v[56:59], v[76:79], v[60:63]
	v_mfma_f32_16x16x32_bf16 v[36:39], v[36:39], v[72:75], v[56:59]
	v_mfma_f32_16x16x32_bf16 v[36:39], v[40:43], v[68:71], v[36:39]
	ds_read_b64_tr_b16 v[40:41], v171 offset:52320
	s_nop 2
	v_mul_f32_e32 v56, v45, v45
	v_fmac_f32_e32 v56, v44, v44
	v_mfma_f32_16x16x32_bf16 v[28:31], v[28:31], v[52:55], v[36:39]
	ds_read_b64_tr_b16 v[42:43], v171 offset:53600
	s_nop 1
	ds_read_b64_tr_b16 v[36:37], v171 offset:62560
	ds_read_b64_tr_b16 v[38:39], v171 offset:63840
	v_mfma_f32_16x16x32_bf16 v[24:27], v[24:27], v[48:51], v[28:31]
	s_waitcnt lgkmcnt(2)
	v_mfma_f32_16x16x32_bf16 v[28:31], v[40:43], v[80:83], 0
	v_mul_f32_e32 v40, v47, v47
	v_fmac_f32_e32 v40, v46, v46
	v_add_f32_e32 v40, v56, v40
	s_waitcnt lgkmcnt(0)
	v_mfma_f32_16x16x32_bf16 v[28:31], v[36:39], v[76:79], v[28:31]
	v_mul_f32_e32 v36, v33, v33
	v_mul_f32_e32 v37, v35, v35
	v_fmac_f32_e32 v36, v32, v32
	v_mfma_f32_16x16x32_bf16 v[20:23], v[20:23], v[72:75], v[28:31]
	v_fmac_f32_e32 v37, v34, v34
	v_mfma_f32_16x16x32_bf16 v[16:19], v[16:19], v[68:71], v[20:23]
	v_add_f32_e32 v28, v36, v37
	v_add_f32_e32 v28, v40, v28
	v_mfma_f32_16x16x32_bf16 v[12:15], v[12:15], v[52:55], v[16:19]
	s_nop 0
	v_mul_f32_e32 v20, v25, v25
	v_mul_f32_e32 v21, v27, v27
	v_fmac_f32_e32 v20, v24, v24
	v_mfma_f32_16x16x32_bf16 v[8:11], v[8:11], v[48:51], v[12:15]
	v_fmac_f32_e32 v21, v26, v26
	v_add_f32_e32 v16, v20, v21
	v_add_f32_e32 v16, v28, v16
	s_nop 4
	v_mul_f32_e32 v12, v9, v9
	v_mul_f32_e32 v13, v11, v11
	v_fmac_f32_e32 v12, v8, v8
	v_fmac_f32_e32 v13, v10, v10
	v_add_f32_e32 v12, v12, v13
	v_mbcnt_lo_u32_b32 v13, s25, 0
	v_mbcnt_hi_u32_b32 v13, s25, v13
	v_lshlrev_b32_e32 v13, 2, v13
	v_add_f32_e32 v12, v16, v12
	v_xor_b32_e32 v13, 64, v13
	ds_bpermute_b32 v13, v13, v12
	s_mov_b32 s25, -1
	s_waitcnt lgkmcnt(0)
	v_add_f32_e32 v12, v12, v13
	v_mbcnt_lo_u32_b32 v13, s25, 0
	v_mbcnt_hi_u32_b32 v13, s25, v13
	v_lshlrev_b32_e32 v13, 2, v13
	v_xor_b32_e32 v13, 0x80, v13
	ds_bpermute_b32 v13, v13, v12
	s_and_saveexec_b64 vcc, s[4:5]
	s_cbranch_execz .LBB0_334
	s_waitcnt lgkmcnt(0)
	v_add_f32_e32 v12, v12, v13
	ds_write_b32 v149, v12
	s_branch .LBB0_334
